# phase 0b norm+modulate: next trip's two rows fetched at the top of a trip into a second register set (loads overlap reduction/rsqrt/stores), on top of P5 prefetch
# speedup vs baseline: 1.0029x; 1.0029x over previous
.LBB0_206:
	s_or_b64 exec, exec, s[0:1]
	s_mov_b64 s[4:5], s[92:93]
	s_waitcnt lgkmcnt(0)
	v_mov_b32_e32 v0, v230
	s_barrier
	v_readlane_b32 s0, v252, 4
	v_ashrrev_i32_e32 v1, 6, v0
	s_mov_b32 s2, 0x10000
	v_add_u32_e32 v54, s0, v1
	v_cmp_gt_i32_e32 vcc, s2, v54
	v_mbcnt_lo_u32_b32 v220, -1, 0
	s_and_saveexec_b64 s[0:1], vcc
	s_cbranch_execz .LBB0_217
	v_and_b32_e32 v2, 63, v0
	v_mbcnt_hi_u32_b32 v0, -1, v220
	v_and_b32_e32 v1, 64, v0
	v_add_u32_e32 v1, 64, v1
	v_xor_b32_e32 v3, 1, v0
	v_cmp_lt_i32_e32 vcc, v3, v1
	s_load_dwordx2 s[6:7], s[4:5], 0xd8
	s_load_dwordx2 s[10:11], s[4:5], 0x0
	s_load_dwordx2 s[12:13], s[4:5], 0x28
	v_cndmask_b32_e32 v3, v0, v3, vcc
	v_lshlrev_b32_e32 v45, 2, v3
	v_xor_b32_e32 v3, 2, v0
	v_cmp_lt_i32_e32 vcc, v3, v1
	v_mov_b32_e32 v37, 0
	s_mov_b64 s[4:5], 0x86a0000
	v_cndmask_b32_e32 v3, v0, v3, vcc
	v_lshlrev_b32_e32 v47, 2, v3
	v_xor_b32_e32 v3, 4, v0
	v_cmp_lt_i32_e32 vcc, v3, v1
	v_lshlrev_b32_e32 v36, 4, v2
	s_waitcnt lgkmcnt(0)
	s_add_u32 s8, s6, 0x3010000
	v_cndmask_b32_e32 v3, v0, v3, vcc
	v_lshlrev_b32_e32 v49, 2, v3
	v_xor_b32_e32 v3, 8, v0
	v_cmp_lt_i32_e32 vcc, v3, v1
	s_addc_u32 s9, s7, 0
	v_lshl_add_u64 v[38:39], s[10:11], 0, v[36:37]
	v_cndmask_b32_e32 v3, v0, v3, vcc
	v_lshlrev_b32_e32 v70, 2, v3
	v_xor_b32_e32 v3, 16, v0
	v_cmp_lt_i32_e32 vcc, v3, v1
	v_lshl_add_u64 v[42:43], s[12:13], 0, v[36:37]
	s_mov_b64 s[10:11], 0
	v_cndmask_b32_e32 v3, v0, v3, vcc
	v_lshlrev_b32_e32 v71, 2, v3
	v_xor_b32_e32 v3, 32, v0
	v_cmp_lt_i32_e32 vcc, v3, v1
	v_mov_b32_e32 v1, v37
	v_mov_b32_e32 v73, 0x358637bd
	v_cndmask_b32_e32 v0, v0, v3, vcc
	v_lshlrev_b32_e32 v72, 2, v0
	v_lshlrev_b32_e32 v0, 3, v2
	v_lshl_add_u64 v[0:1], s[6:7], 0, v[0:1]
	v_lshl_add_u64 v[40:41], v[0:1], 0, s[4:5]
	v_lshlrev_b32_e32 v0, 2, v2
	v_lshlrev_b32_e32 v50, 2, v0
	v_or_b32_e32 v44, 0x100, v0
	v_or_b32_e32 v46, 0x200, v0
	v_or_b32_e32 v48, 0x300, v0
	s_mov_b32 s3, 0xf800000
	v_mov_b32_e32 v74, 0x260
	s_mov_b64 s[12:13], 0x1000
	v_mov_b32_e32 v52, v50
	v_mov_b32_e32 v53, v37
	s_mov_b32 s14, 0xffff
	v_mov_b32_e32 v202, v54
	v_add_u32_e32 v204, s94, v54
	v_ashrrev_i32_e32 v203, 31, v54
	v_cmp_gt_i32_e64 s[22:23], s2, v204
	v_lshlrev_b64 v[206:207], 12, v[202:203]
	v_lshl_add_u64 v[206:207], v[38:39], 0, v[206:207]
	global_load_dwordx4 v[198:201], v[206:207], off nt
	global_load_dwordx4 v[148:151], v[206:207], off offset:1024 nt
	global_load_dwordx4 v[132:135], v[206:207], off offset:3072 nt
	global_load_dwordx4 v[140:143], v[206:207], off offset:2048 nt
	v_cndmask_b32_e64 v204, v202, v204, s[22:23]
	v_ashrrev_i32_e32 v205, 31, v204
	v_lshlrev_b64 v[208:209], 12, v[204:205]
	v_lshl_add_u64 v[208:209], v[38:39], 0, v[208:209]
	global_load_dwordx4 v[152:155], v[208:209], off nt
	global_load_dwordx4 v[144:147], v[208:209], off offset:1024 nt
	global_load_dwordx4 v[128:131], v[208:209], off offset:3072 nt
	global_load_dwordx4 v[136:139], v[208:209], off offset:2048 nt
	s_waitcnt vmcnt(0)
	s_branch .LBB0_209

.LBB0_209:
	v_ashrrev_i32_e32 v55, 31, v54
	v_add_u32_e32 v75, s94, v54
	v_cmp_gt_i32_e32 vcc, s2, v75
	s_waitcnt vmcnt(8)
	v_mov_b64_e32 v[0:1], v[128:129]
	v_mov_b64_e32 v[2:3], v[130:131]
	v_mov_b64_e32 v[4:5], v[132:133]
	v_mov_b64_e32 v[6:7], v[134:135]
	v_mov_b64_e32 v[8:9], v[136:137]
	v_mov_b64_e32 v[10:11], v[138:139]
	v_mov_b64_e32 v[12:13], v[140:141]
	v_mov_b64_e32 v[14:15], v[142:143]
	v_mov_b64_e32 v[16:17], v[144:145]
	v_mov_b64_e32 v[18:19], v[146:147]
	v_mov_b64_e32 v[20:21], v[148:149]
	v_mov_b64_e32 v[22:23], v[150:151]
	v_mov_b64_e32 v[24:25], v[152:153]
	v_mov_b64_e32 v[26:27], v[154:155]
	v_mov_b64_e32 v[28:29], v[198:199]
	v_mov_b64_e32 v[30:31], v[200:201]
	v_cndmask_b32_e32 v56, v54, v75, vcc
	v_ashrrev_i32_e32 v57, 31, v56
	v_add_u32_e32 v202, s94, v75
	v_cmp_ge_i32_e64 s[22:23], s14, v202
	v_add_u32_e32 v204, s94, v202
	v_ashrrev_i32_e32 v203, 31, v202
	s_and_saveexec_b64 s[24:25], s[22:23]
	s_cbranch_execz .Lp0pf_skip
	v_cmp_gt_i32_e64 s[22:23], s2, v204
	v_lshlrev_b64 v[206:207], 12, v[202:203]
	v_lshl_add_u64 v[206:207], v[38:39], 0, v[206:207]
	global_load_dwordx4 v[198:201], v[206:207], off nt
	global_load_dwordx4 v[148:151], v[206:207], off offset:1024 nt
	global_load_dwordx4 v[132:135], v[206:207], off offset:3072 nt
	global_load_dwordx4 v[140:143], v[206:207], off offset:2048 nt
	v_cndmask_b32_e64 v204, v202, v204, s[22:23]
	v_ashrrev_i32_e32 v205, 31, v204
	v_lshlrev_b64 v[208:209], 12, v[204:205]
	v_lshl_add_u64 v[208:209], v[38:39], 0, v[208:209]
	global_load_dwordx4 v[152:155], v[208:209], off nt
	global_load_dwordx4 v[144:147], v[208:209], off offset:1024 nt
	global_load_dwordx4 v[128:131], v[208:209], off offset:3072 nt
	global_load_dwordx4 v[136:139], v[208:209], off offset:2048 nt
.Lp0pf_skip:
	s_mov_b64 exec, s[24:25]
	v_pk_mul_f32 v[32:33], v[30:31], v[30:31]
	v_pk_mul_f32 v[34:35], v[28:29], v[28:29]
	v_pk_mul_f32 v[58:59], v[22:23], v[22:23]
	v_pk_mul_f32 v[60:61], v[20:21], v[20:21]
	v_mul_f32_e32 v62, v15, v15
	v_pk_mov_b32 v[64:65], v[34:35], v[32:33] op_sel:[1,0]
	v_mov_b32_e32 v35, v33
	v_pk_mov_b32 v[32:33], v[60:61], v[58:59] op_sel:[1,0]
	v_mov_b32_e32 v61, v59
	v_mul_f32_e32 v78, v7, v7
	v_mul_f32_e32 v36, v13, v13
	v_pk_fma_f32 v[62:63], v[14:15], v[14:15], v[62:63] op_sel_hi:[1,1,0]
	v_pk_add_f32 v[34:35], v[64:65], v[34:35]
	v_pk_mul_f32 v[64:65], v[26:27], v[26:27]
	v_pk_mul_f32 v[66:67], v[24:25], v[24:25]
	v_pk_add_f32 v[32:33], v[32:33], v[60:61]
	v_pk_mul_f32 v[60:61], v[18:19], v[18:19]
	v_pk_mul_f32 v[68:69], v[16:17], v[16:17]
	v_mul_f32_e32 v51, v4, v4
	v_mul_f32_e32 v77, v5, v5
	v_mul_f32_e32 v76, v6, v6
	v_pk_fma_f32 v[58:59], v[12:13], v[12:13], v[36:37] op_sel_hi:[1,1,0]
	v_mov_b32_e32 v63, v78
	v_pk_mov_b32 v[78:79], v[66:67], v[64:65] op_sel:[1,0]
	v_mov_b32_e32 v67, v65
	v_pk_mov_b32 v[64:65], v[68:69], v[60:61] op_sel:[1,0]
	v_mov_b32_e32 v69, v61
	v_pk_add_f32 v[34:35], v[34:35], v[34:35] op_sel:[0,1] op_sel_hi:[1,0]
	v_pk_add_f32 v[32:33], v[32:33], v[32:33] op_sel:[0,1] op_sel_hi:[1,0]
	v_mov_b32_e32 v59, v76
	v_mul_f32_e32 v36, v9, v9
	v_mul_f32_e32 v76, v11, v11
	v_pk_add_f32 v[66:67], v[78:79], v[66:67]
	v_pk_add_f32 v[64:65], v[64:65], v[68:69]
	v_mov_b32_e32 v35, v51
	v_mov_b32_e32 v33, v77
	v_mul_f32_e32 v80, v0, v0
	v_mul_f32_e32 v81, v1, v1
	v_mul_f32_e32 v82, v2, v2
	v_mul_f32_e32 v83, v3, v3
	v_pk_add_f32 v[58:59], v[58:59], v[62:63]
	v_pk_fma_f32 v[60:61], v[8:9], v[8:9], v[36:37] op_sel_hi:[1,1,0]
	v_pk_fma_f32 v[62:63], v[10:11], v[10:11], v[76:77] op_sel_hi:[1,1,0]
	v_pk_add_f32 v[32:33], v[34:35], v[32:33]
	v_pk_add_f32 v[34:35], v[66:67], v[66:67] op_sel:[0,1] op_sel_hi:[1,0]
	v_pk_add_f32 v[64:65], v[64:65], v[64:65] op_sel:[0,1] op_sel_hi:[1,0]
	v_mov_b32_e32 v61, v82
	v_mov_b32_e32 v63, v83
	v_pk_add_f32 v[32:33], v[32:33], v[58:59]
	v_mov_b32_e32 v35, v80
	v_mov_b32_e32 v65, v81
	v_pk_add_f32 v[60:61], v[60:61], v[62:63]
	v_add_f32_e32 v36, v32, v33
	v_pk_add_f32 v[32:33], v[34:35], v[64:65]
	ds_bpermute_b32 v34, v45, v36
	v_pk_add_f32 v[32:33], v[32:33], v[60:61]
	v_ashrrev_i32_e32 v58, 12, v54
	v_add_f32_e32 v32, v32, v33
	ds_bpermute_b32 v33, v45, v32
	v_mul_hi_i32_i24_e32 v59, 0x9000, v58
	v_mul_i32_i24_e32 v58, 0x9000, v58
	s_waitcnt lgkmcnt(1)
	v_add_f32_e32 v36, v36, v34
	ds_bpermute_b32 v51, v47, v36
	s_waitcnt lgkmcnt(1)
	v_add_f32_e32 v60, v32, v33
	ds_bpermute_b32 v61, v47, v60
	global_load_dwordx4 v[32:35], v[42:43], off
	s_waitcnt lgkmcnt(1)
	v_add_f32_e32 v36, v36, v51
	ds_bpermute_b32 v51, v49, v36
	s_waitcnt lgkmcnt(1)
	v_add_f32_e32 v62, v60, v61
	ds_bpermute_b32 v63, v49, v62
	v_lshl_add_u64 v[60:61], s[8:9], 0, v[58:59]
	v_lshl_add_u64 v[58:59], v[60:61], 0, s[12:13]
	v_lshl_add_u64 v[60:61], v[60:61], 0, v[52:53]
	global_load_dwordx4 v[76:79], v[60:61], off
	s_waitcnt lgkmcnt(0)
	v_add_f32_e32 v62, v62, v63
	ds_bpermute_b32 v63, v70, v62
	v_add_f32_e32 v36, v36, v51
	ds_bpermute_b32 v51, v70, v36
	s_waitcnt lgkmcnt(1)
	v_add_f32_e32 v64, v62, v63
	v_lshl_add_u64 v[62:63], v[58:59], 0, v[52:53]
	global_load_dwordx4 v[80:83], v[62:63], off
	global_load_dwordx4 v[84:87], v[42:43], off offset:1024
	global_load_dwordx4 v[96:99], v[62:63], off offset:1024
	global_load_dwordx4 v[108:111], v[60:61], off offset:1024
	global_load_dwordx4 v[88:91], v[42:43], off offset:2048
	global_load_dwordx4 v[100:103], v[62:63], off offset:2048
	global_load_dwordx4 v[112:115], v[60:61], off offset:2048
	global_load_dwordx4 v[92:95], v[42:43], off offset:3072
	global_load_dwordx4 v[104:107], v[62:63], off offset:3072
	global_load_dwordx4 v[116:119], v[60:61], off offset:3072
	s_waitcnt lgkmcnt(0)
	v_add_f32_e32 v36, v36, v51
	ds_bpermute_b32 v51, v71, v36
	ds_bpermute_b32 v65, v71, v64
	s_waitcnt lgkmcnt(1)
	v_add_f32_e32 v36, v36, v51
	ds_bpermute_b32 v51, v72, v36
	s_waitcnt lgkmcnt(1)
	v_add_f32_e32 v64, v64, v65
	ds_bpermute_b32 v65, v72, v64
	s_waitcnt lgkmcnt(1)
	v_add_f32_e32 v36, v36, v51
	v_fmamk_f32 v36, v36, 0x3a800000, v73
	v_mul_f32_e32 v51, 0x4f800000, v36
	v_cmp_gt_f32_e32 vcc, s3, v36
	s_waitcnt lgkmcnt(0)
	v_add_f32_e32 v62, v64, v65
	v_cndmask_b32_e32 v36, v36, v51, vcc
	v_fmamk_f32 v51, v62, 0x3a800000, v73
	v_sqrt_f32_e32 v62, v36
	v_mul_f32_e32 v63, 0x4f800000, v51
	v_cmp_gt_f32_e64 s[4:5], s3, v51
	v_add_u32_e32 v64, -1, v62
	v_cndmask_b32_e64 v51, v51, v63, s[4:5]
	v_sqrt_f32_e32 v63, v51
	v_add_u32_e32 v65, 1, v62
	v_fma_f32 v66, -v64, v62, v36
	v_fma_f32 v67, -v65, v62, v36
	v_cmp_ge_f32_e64 s[6:7], 0, v66
	v_add_u32_e32 v66, 1, v63
	s_nop 0
	v_cndmask_b32_e64 v62, v62, v64, s[6:7]
	v_add_u32_e32 v64, -1, v63
	v_cmp_lt_f32_e64 s[6:7], 0, v67
	v_fma_f32 v67, -v66, v63, v51
	s_nop 0
	v_cndmask_b32_e64 v62, v62, v65, s[6:7]
	v_fma_f32 v65, -v64, v63, v51
	v_mul_f32_e32 v68, 0x37800000, v62
	v_cmp_ge_f32_e64 s[6:7], 0, v65
	v_cndmask_b32_e32 v62, v62, v68, vcc
	v_cmp_lt_f32_e32 vcc, 0, v67
	v_cndmask_b32_e64 v63, v63, v64, s[6:7]
	s_nop 0
	v_cndmask_b32_e32 v63, v63, v66, vcc
	v_cmp_class_f32_e32 vcc, v36, v74
	s_nop 1
	v_cndmask_b32_e32 v36, v62, v36, vcc
	v_div_scale_f32 v64, s[6:7], v36, v36, 1.0
	v_rcp_f32_e32 v66, v64
	v_mul_f32_e32 v62, 0x37800000, v63
	v_cndmask_b32_e64 v62, v63, v62, s[4:5]
	v_cmp_class_f32_e64 s[4:5], v51, v74
	v_div_scale_f32 v65, vcc, 1.0, v36, 1.0
	s_nop 0
	v_cndmask_b32_e64 v51, v62, v51, s[4:5]
	v_fma_f32 v62, -v64, v66, 1.0
	v_fmac_f32_e32 v66, v62, v66
	v_mul_f32_e32 v62, v65, v66
	v_fma_f32 v63, -v64, v62, v65
	v_fmac_f32_e32 v62, v63, v66
	v_fma_f32 v63, -v64, v62, v65
	v_div_scale_f32 v64, s[4:5], v51, v51, 1.0
	v_rcp_f32_e32 v65, v64
	v_div_fmas_f32 v62, v63, v66, v62
	v_div_fixup_f32 v68, v62, v36, 1.0
	v_fma_f32 v36, -v64, v65, 1.0
	v_fmac_f32_e32 v65, v36, v65
	v_div_scale_f32 v36, vcc, 1.0, v51, 1.0
	v_mul_f32_e32 v62, v36, v65
	v_fma_f32 v63, -v64, v62, v36
	v_fmac_f32_e32 v62, v63, v65
	v_fma_f32 v36, -v64, v62, v36
	v_div_fmas_f32 v36, v36, v65, v62
	v_div_fixup_f32 v64, v36, v51, 1.0
	v_lshlrev_b64 v[124:125], 11, v[54:55]
	v_lshlrev_b64 v[126:127], 11, v[56:57]
	v_mov_b32_e32 v120, v68
	v_mov_b32_e32 v122, v64
	v_lshl_add_u64 v[124:125], v[40:41], 0, v[124:125]
	v_lshl_add_u64 v[126:127], v[40:41], 0, v[126:127]
	s_waitcnt vmcnt(0)
	v_pk_add_f32 v[80:81], v[80:81], 1.0 op_sel_hi:[1,0]
	v_pk_add_f32 v[82:83], v[82:83], 1.0 op_sel_hi:[1,0]
	v_pk_mul_f32 v[28:29], v[28:29], v[120:121] op_sel_hi:[1,0]
	v_pk_mul_f32 v[30:31], v[30:31], v[120:121] op_sel_hi:[1,0]
	v_pk_mul_f32 v[28:29], v[32:33], v[28:29]
	v_pk_mul_f32 v[30:31], v[34:35], v[30:31]
	v_pk_fma_f32 v[28:29], v[80:81], v[28:29], v[76:77]
	v_pk_fma_f32 v[30:31], v[82:83], v[30:31], v[78:79]
	v_cvt_pk_bf16_f32 v28, v28, v29
	v_cvt_pk_bf16_f32 v29, v30, v31
	global_store_dwordx2 v[124:125], v[28:29], off
	v_pk_mul_f32 v[24:25], v[24:25], v[122:123] op_sel_hi:[1,0]
	v_pk_mul_f32 v[26:27], v[26:27], v[122:123] op_sel_hi:[1,0]
	v_pk_mul_f32 v[24:25], v[32:33], v[24:25]
	v_pk_mul_f32 v[26:27], v[34:35], v[26:27]
	v_pk_fma_f32 v[24:25], v[80:81], v[24:25], v[76:77]
	v_pk_fma_f32 v[26:27], v[82:83], v[26:27], v[78:79]
	v_cvt_pk_bf16_f32 v24, v24, v25
	v_cvt_pk_bf16_f32 v25, v26, v27
	global_store_dwordx2 v[126:127], v[24:25], off
	v_pk_add_f32 v[96:97], v[96:97], 1.0 op_sel_hi:[1,0]
	v_pk_add_f32 v[98:99], v[98:99], 1.0 op_sel_hi:[1,0]
	v_pk_mul_f32 v[20:21], v[20:21], v[120:121] op_sel_hi:[1,0]
	v_pk_mul_f32 v[22:23], v[22:23], v[120:121] op_sel_hi:[1,0]
	v_pk_mul_f32 v[20:21], v[84:85], v[20:21]
	v_pk_mul_f32 v[22:23], v[86:87], v[22:23]
	v_pk_fma_f32 v[20:21], v[96:97], v[20:21], v[108:109]
	v_pk_fma_f32 v[22:23], v[98:99], v[22:23], v[110:111]
	v_cvt_pk_bf16_f32 v20, v20, v21
	v_cvt_pk_bf16_f32 v21, v22, v23
	global_store_dwordx2 v[124:125], v[20:21], off offset:512
	v_pk_mul_f32 v[16:17], v[16:17], v[122:123] op_sel_hi:[1,0]
	v_pk_mul_f32 v[18:19], v[18:19], v[122:123] op_sel_hi:[1,0]
	v_pk_mul_f32 v[16:17], v[84:85], v[16:17]
	v_pk_mul_f32 v[18:19], v[86:87], v[18:19]
	v_pk_fma_f32 v[16:17], v[96:97], v[16:17], v[108:109]
	v_pk_fma_f32 v[18:19], v[98:99], v[18:19], v[110:111]
	v_cvt_pk_bf16_f32 v16, v16, v17
	v_cvt_pk_bf16_f32 v17, v18, v19
	global_store_dwordx2 v[126:127], v[16:17], off offset:512
	v_pk_add_f32 v[100:101], v[100:101], 1.0 op_sel_hi:[1,0]
	v_pk_add_f32 v[102:103], v[102:103], 1.0 op_sel_hi:[1,0]
	v_pk_mul_f32 v[12:13], v[12:13], v[120:121] op_sel_hi:[1,0]
	v_pk_mul_f32 v[14:15], v[14:15], v[120:121] op_sel_hi:[1,0]
	v_pk_mul_f32 v[12:13], v[88:89], v[12:13]
	v_pk_mul_f32 v[14:15], v[90:91], v[14:15]
	v_pk_fma_f32 v[12:13], v[100:101], v[12:13], v[112:113]
	v_pk_fma_f32 v[14:15], v[102:103], v[14:15], v[114:115]
	v_cvt_pk_bf16_f32 v12, v12, v13
	v_cvt_pk_bf16_f32 v13, v14, v15
	global_store_dwordx2 v[124:125], v[12:13], off offset:1024
	v_pk_mul_f32 v[8:9], v[8:9], v[122:123] op_sel_hi:[1,0]
	v_pk_mul_f32 v[10:11], v[10:11], v[122:123] op_sel_hi:[1,0]
	v_pk_mul_f32 v[8:9], v[88:89], v[8:9]
	v_pk_mul_f32 v[10:11], v[90:91], v[10:11]
	v_pk_fma_f32 v[8:9], v[100:101], v[8:9], v[112:113]
	v_pk_fma_f32 v[10:11], v[102:103], v[10:11], v[114:115]
	v_cvt_pk_bf16_f32 v8, v8, v9
	v_cvt_pk_bf16_f32 v9, v10, v11
	global_store_dwordx2 v[126:127], v[8:9], off offset:1024
	v_pk_add_f32 v[104:105], v[104:105], 1.0 op_sel_hi:[1,0]
	v_pk_add_f32 v[106:107], v[106:107], 1.0 op_sel_hi:[1,0]
	v_pk_mul_f32 v[4:5], v[4:5], v[120:121] op_sel_hi:[1,0]
	v_pk_mul_f32 v[6:7], v[6:7], v[120:121] op_sel_hi:[1,0]
	v_pk_mul_f32 v[4:5], v[92:93], v[4:5]
	v_pk_mul_f32 v[6:7], v[94:95], v[6:7]
	v_pk_fma_f32 v[4:5], v[104:105], v[4:5], v[116:117]
	v_pk_fma_f32 v[6:7], v[106:107], v[6:7], v[118:119]
	v_cvt_pk_bf16_f32 v4, v4, v5
	v_cvt_pk_bf16_f32 v5, v6, v7
	global_store_dwordx2 v[124:125], v[4:5], off offset:1536
	v_pk_mul_f32 v[0:1], v[0:1], v[122:123] op_sel_hi:[1,0]
	v_pk_mul_f32 v[2:3], v[2:3], v[122:123] op_sel_hi:[1,0]
	v_pk_mul_f32 v[0:1], v[92:93], v[0:1]
	v_pk_mul_f32 v[2:3], v[94:95], v[2:3]
	v_pk_fma_f32 v[0:1], v[104:105], v[0:1], v[116:117]
	v_pk_fma_f32 v[2:3], v[106:107], v[2:3], v[118:119]
	v_cvt_pk_bf16_f32 v0, v0, v1
	v_cvt_pk_bf16_f32 v1, v2, v3
	global_store_dwordx2 v[126:127], v[0:1], off offset:1536
	s_mov_b64 s[4:5], exec
	s_branch .LBB0_208
